# E/H residual epilogue rewritten by hand: base loads software-pipelined 4 steps ahead with counted vmcnt, saddr+voffset addressing, permlane-swap ssq reduce
# speedup vs baseline: 1.0081x; 1.0081x over previous
.LBB0_522:
	s_load_dwordx2 s[48:49], s[46:47], 0x18
	v_lshl_add_u32 v170, s53, 8, v149
	v_lshl_or_b32 v168, s52, 8, v173
	v_lshlrev_b32_e32 v199, 11, v170
	v_add_lshl_u32 v199, v199, v168, 2
	v_lshlrev_b32_e32 v200, 2, v168
	v_lshlrev_b32_e32 v201, 7, v170
	s_waitcnt lgkmcnt(0)
	s_add_u32 s46, s50, 0xdf00000
	s_addc_u32 s47, s51, 0
	s_add_u32 s48, s48, s37
	s_addc_u32 s49, s49, 0
	s_add_u32 s98, s50, 0x9f00000
	s_addc_u32 s99, s51, 0
	s_lshl_b32 s52, s52, 2
	s_ashr_i32 s53, s52, 31
	s_lshl_b64 s[52:53], s[52:53], 2
	s_add_u32 s13, s50, s52
	s_addc_u32 s21, s51, s53
	s_add_u32 s13, s13, s54
	s_addc_u32 s21, s21, 0
	s_add_u32 s50, s13, 0x1a700000
	s_addc_u32 s51, s21, 0
	global_load_dwordx4 v[102:105], v200, s[48:49]
	global_load_dwordx4 v[98:101], v200, s[48:49] offset:16
	global_load_dwordx4 v[86:89], v200, s[48:49] offset:512
	global_load_dwordx4 v[82:85], v200, s[48:49] offset:528
	v_mov_b32_e32 v154, v199
	global_load_dwordx4 v[210:213], v154, s[44:45]
	global_load_dwordx4 v[214:217], v154, s[44:45] offset:16
	global_load_dwordx4 v[218:221], v154, s[44:45] offset:512
	global_load_dwordx4 v[222:225], v154, s[44:45] offset:528
	v_add_u32_e32 v155, 0x20000, v199
	global_load_dwordx4 v[226:229], v155, s[44:45]
	global_load_dwordx4 v[236:239], v155, s[44:45] offset:16
	global_load_dwordx4 v[240:243], v155, s[44:45] offset:512
	global_load_dwordx4 v[244:247], v155, s[44:45] offset:528
	v_add_u32_e32 v156, 0x40000, v199
	global_load_dwordx4 v[180:183], v156, s[44:45]
	global_load_dwordx4 v[184:187], v156, s[44:45] offset:16
	s_waitcnt vmcnt(8)
	v_pk_add_f32 v[142:143], v[142:143], v[210:211]
	v_pk_add_f32 v[144:145], v[144:145], v[212:213]
	v_pk_add_f32 v[138:139], v[138:139], v[214:215]
	v_pk_add_f32 v[140:141], v[140:141], v[216:217]
	global_store_dwordx4 v154, v[142:145], s[98:99]
	global_store_dwordx4 v154, v[138:141], s[98:99] offset:16
	v_pk_mul_f32 v[210:211], v[102:103], v[142:143]
	v_pk_mul_f32 v[212:213], v[104:105], v[144:145]
	v_pk_mul_f32 v[214:215], v[98:99], v[138:139]
	v_pk_mul_f32 v[216:217], v[100:101], v[140:141]
	v_cvt_pk_bf16_f32 v188, v210, v211
	v_cvt_pk_bf16_f32 v189, v212, v213
	v_cvt_pk_bf16_f32 v190, v214, v215
	v_cvt_pk_bf16_f32 v191, v216, v217
	v_lshrrev_b32_e32 v202, 1, v154
	global_store_dwordx4 v202, v[188:191], s[46:47]
	v_mul_f32_e32 v196, v142, v142
	v_fmac_f32_e32 v196, v143, v143
	v_fmac_f32_e32 v196, v144, v144
	v_fmac_f32_e32 v196, v145, v145
	v_fmac_f32_e32 v196, v138, v138
	v_fmac_f32_e32 v196, v139, v139
	v_fmac_f32_e32 v196, v140, v140
	v_fmac_f32_e32 v196, v141, v141
	global_load_dwordx4 v[210:213], v156, s[44:45] offset:512
	global_load_dwordx4 v[214:217], v156, s[44:45] offset:528
	s_waitcnt vmcnt(11)
	v_pk_add_f32 v[134:135], v[134:135], v[218:219]
	v_pk_add_f32 v[136:137], v[136:137], v[220:221]
	v_pk_add_f32 v[130:131], v[130:131], v[222:223]
	v_pk_add_f32 v[132:133], v[132:133], v[224:225]
	global_store_dwordx4 v154, v[134:137], s[98:99] offset:512
	global_store_dwordx4 v154, v[130:133], s[98:99] offset:528
	v_pk_mul_f32 v[218:219], v[86:87], v[134:135]
	v_pk_mul_f32 v[220:221], v[88:89], v[136:137]
	v_pk_mul_f32 v[222:223], v[82:83], v[130:131]
	v_pk_mul_f32 v[224:225], v[84:85], v[132:133]
	v_cvt_pk_bf16_f32 v192, v218, v219
	v_cvt_pk_bf16_f32 v193, v220, v221
	v_cvt_pk_bf16_f32 v194, v222, v223
	v_cvt_pk_bf16_f32 v195, v224, v225
	global_store_dwordx4 v202, v[192:195], s[46:47] offset:256
	v_fmac_f32_e32 v196, v134, v134
	v_fmac_f32_e32 v196, v135, v135
	v_fmac_f32_e32 v196, v136, v136
	v_fmac_f32_e32 v196, v137, v137
	v_fmac_f32_e32 v196, v130, v130
	v_fmac_f32_e32 v196, v131, v131
	v_fmac_f32_e32 v196, v132, v132
	v_fmac_f32_e32 v196, v133, v133
	v_mov_b32_e32 v198, v196
	s_nop 1
	v_permlane16_swap_b32_e32 v196, v198
	v_add_f32_e32 v196, v196, v198
	v_mov_b32_e32 v198, v196
	s_nop 1
	v_permlane32_swap_b32_e32 v196, v198
	v_add_f32_e32 v196, v196, v198
	v_mov_b32_e32 v200, v201
	s_mov_b64 exec, s[38:39]
	global_store_dword v200, v196, s[50:51]
	s_mov_b64 exec, -1
	v_add_u32_e32 v157, 0x60000, v199
	global_load_dwordx4 v[218:221], v157, s[44:45]
	global_load_dwordx4 v[222:225], v157, s[44:45] offset:16
	s_waitcnt vmcnt(15)
	v_pk_add_f32 v[126:127], v[126:127], v[226:227]
	v_pk_add_f32 v[128:129], v[128:129], v[228:229]
	v_pk_add_f32 v[122:123], v[122:123], v[236:237]
	v_pk_add_f32 v[124:125], v[124:125], v[238:239]
	global_store_dwordx4 v155, v[126:129], s[98:99]
	global_store_dwordx4 v155, v[122:125], s[98:99] offset:16
	v_pk_mul_f32 v[226:227], v[102:103], v[126:127]
	v_pk_mul_f32 v[228:229], v[104:105], v[128:129]
	v_pk_mul_f32 v[236:237], v[98:99], v[122:123]
	v_pk_mul_f32 v[238:239], v[100:101], v[124:125]
	v_cvt_pk_bf16_f32 v188, v226, v227
	v_cvt_pk_bf16_f32 v189, v228, v229
	v_cvt_pk_bf16_f32 v190, v236, v237
	v_cvt_pk_bf16_f32 v191, v238, v239
	v_lshrrev_b32_e32 v203, 1, v155
	global_store_dwordx4 v203, v[188:191], s[46:47]
	v_mul_f32_e32 v197, v126, v126
	v_fmac_f32_e32 v197, v127, v127
	v_fmac_f32_e32 v197, v128, v128
	v_fmac_f32_e32 v197, v129, v129
	v_fmac_f32_e32 v197, v122, v122
	v_fmac_f32_e32 v197, v123, v123
	v_fmac_f32_e32 v197, v124, v124
	v_fmac_f32_e32 v197, v125, v125
	global_load_dwordx4 v[226:229], v157, s[44:45] offset:512
	global_load_dwordx4 v[236:239], v157, s[44:45] offset:528
	s_waitcnt vmcnt(18)
	v_pk_add_f32 v[118:119], v[118:119], v[240:241]
	v_pk_add_f32 v[120:121], v[120:121], v[242:243]
	v_pk_add_f32 v[114:115], v[114:115], v[244:245]
	v_pk_add_f32 v[116:117], v[116:117], v[246:247]
	global_store_dwordx4 v155, v[118:121], s[98:99] offset:512
	global_store_dwordx4 v155, v[114:117], s[98:99] offset:528
	v_pk_mul_f32 v[240:241], v[86:87], v[118:119]
	v_pk_mul_f32 v[242:243], v[88:89], v[120:121]
	v_pk_mul_f32 v[244:245], v[82:83], v[114:115]
	v_pk_mul_f32 v[246:247], v[84:85], v[116:117]
	v_cvt_pk_bf16_f32 v192, v240, v241
	v_cvt_pk_bf16_f32 v193, v242, v243
	v_cvt_pk_bf16_f32 v194, v244, v245
	v_cvt_pk_bf16_f32 v195, v246, v247
	global_store_dwordx4 v203, v[192:195], s[46:47] offset:256
	v_fmac_f32_e32 v197, v118, v118
	v_fmac_f32_e32 v197, v119, v119
	v_fmac_f32_e32 v197, v120, v120
	v_fmac_f32_e32 v197, v121, v121
	v_fmac_f32_e32 v197, v114, v114
	v_fmac_f32_e32 v197, v115, v115
	v_fmac_f32_e32 v197, v116, v116
	v_fmac_f32_e32 v197, v117, v117
	v_mov_b32_e32 v198, v197
	s_nop 1
	v_permlane16_swap_b32_e32 v197, v198
	v_add_f32_e32 v197, v197, v198
	v_mov_b32_e32 v198, v197
	s_nop 1
	v_permlane32_swap_b32_e32 v197, v198
	v_add_f32_e32 v197, v197, v198
	v_add_u32_e32 v200, 0x800, v201
	s_mov_b64 exec, s[38:39]
	global_store_dword v200, v197, s[50:51]
	s_mov_b64 exec, -1
	v_add_u32_e32 v154, 0x100000, v199
	global_load_dwordx4 v[240:243], v154, s[44:45]
	global_load_dwordx4 v[244:247], v154, s[44:45] offset:16
	s_waitcnt vmcnt(22)
	v_pk_add_f32 v[110:111], v[110:111], v[180:181]
	v_pk_add_f32 v[112:113], v[112:113], v[182:183]
	v_pk_add_f32 v[106:107], v[106:107], v[184:185]
	v_pk_add_f32 v[108:109], v[108:109], v[186:187]
	global_store_dwordx4 v156, v[110:113], s[98:99]
	global_store_dwordx4 v156, v[106:109], s[98:99] offset:16
	v_pk_mul_f32 v[180:181], v[102:103], v[110:111]
	v_pk_mul_f32 v[182:183], v[104:105], v[112:113]
	v_pk_mul_f32 v[184:185], v[98:99], v[106:107]
	v_pk_mul_f32 v[186:187], v[100:101], v[108:109]
	v_cvt_pk_bf16_f32 v188, v180, v181
	v_cvt_pk_bf16_f32 v189, v182, v183
	v_cvt_pk_bf16_f32 v190, v184, v185
	v_cvt_pk_bf16_f32 v191, v186, v187
	v_lshrrev_b32_e32 v202, 1, v156
	global_store_dwordx4 v202, v[188:191], s[46:47]
	v_mul_f32_e32 v196, v110, v110
	v_fmac_f32_e32 v196, v111, v111
	v_fmac_f32_e32 v196, v112, v112
	v_fmac_f32_e32 v196, v113, v113
	v_fmac_f32_e32 v196, v106, v106
	v_fmac_f32_e32 v196, v107, v107
	v_fmac_f32_e32 v196, v108, v108
	v_fmac_f32_e32 v196, v109, v109
	global_load_dwordx4 v[180:183], v154, s[44:45] offset:512
	global_load_dwordx4 v[184:187], v154, s[44:45] offset:528
	s_waitcnt vmcnt(22)
	v_pk_add_f32 v[94:95], v[94:95], v[210:211]
	v_pk_add_f32 v[96:97], v[96:97], v[212:213]
	v_pk_add_f32 v[90:91], v[90:91], v[214:215]
	v_pk_add_f32 v[92:93], v[92:93], v[216:217]
	global_store_dwordx4 v156, v[94:97], s[98:99] offset:512
	global_store_dwordx4 v156, v[90:93], s[98:99] offset:528
	v_pk_mul_f32 v[210:211], v[86:87], v[94:95]
	v_pk_mul_f32 v[212:213], v[88:89], v[96:97]
	v_pk_mul_f32 v[214:215], v[82:83], v[90:91]
	v_pk_mul_f32 v[216:217], v[84:85], v[92:93]
	v_cvt_pk_bf16_f32 v192, v210, v211
	v_cvt_pk_bf16_f32 v193, v212, v213
	v_cvt_pk_bf16_f32 v194, v214, v215
	v_cvt_pk_bf16_f32 v195, v216, v217
	global_store_dwordx4 v202, v[192:195], s[46:47] offset:256
	v_fmac_f32_e32 v196, v94, v94
	v_fmac_f32_e32 v196, v95, v95
	v_fmac_f32_e32 v196, v96, v96
	v_fmac_f32_e32 v196, v97, v97
	v_fmac_f32_e32 v196, v90, v90
	v_fmac_f32_e32 v196, v91, v91
	v_fmac_f32_e32 v196, v92, v92
	v_fmac_f32_e32 v196, v93, v93
	v_mov_b32_e32 v198, v196
	s_nop 1
	v_permlane16_swap_b32_e32 v196, v198
	v_add_f32_e32 v196, v196, v198
	v_mov_b32_e32 v198, v196
	s_nop 1
	v_permlane32_swap_b32_e32 v196, v198
	v_add_f32_e32 v196, v196, v198
	v_add_u32_e32 v200, 0x1000, v201
	s_mov_b64 exec, s[38:39]
	global_store_dword v200, v196, s[50:51]
	s_mov_b64 exec, -1
	v_add_u32_e32 v155, 0x120000, v199
	global_load_dwordx4 v[210:213], v155, s[44:45]
	global_load_dwordx4 v[214:217], v155, s[44:45] offset:16
	s_waitcnt vmcnt(22)
	v_pk_add_f32 v[78:79], v[78:79], v[218:219]
	v_pk_add_f32 v[80:81], v[80:81], v[220:221]
	v_pk_add_f32 v[74:75], v[74:75], v[222:223]
	v_pk_add_f32 v[76:77], v[76:77], v[224:225]
	global_store_dwordx4 v157, v[78:81], s[98:99]
	global_store_dwordx4 v157, v[74:77], s[98:99] offset:16
	v_pk_mul_f32 v[218:219], v[102:103], v[78:79]
	v_pk_mul_f32 v[220:221], v[104:105], v[80:81]
	v_pk_mul_f32 v[222:223], v[98:99], v[74:75]
	v_pk_mul_f32 v[224:225], v[100:101], v[76:77]
	v_cvt_pk_bf16_f32 v188, v218, v219
	v_cvt_pk_bf16_f32 v189, v220, v221
	v_cvt_pk_bf16_f32 v190, v222, v223
	v_cvt_pk_bf16_f32 v191, v224, v225
	v_lshrrev_b32_e32 v203, 1, v157
	global_store_dwordx4 v203, v[188:191], s[46:47]
	v_mul_f32_e32 v197, v78, v78
	v_fmac_f32_e32 v197, v79, v79
	v_fmac_f32_e32 v197, v80, v80
	v_fmac_f32_e32 v197, v81, v81
	v_fmac_f32_e32 v197, v74, v74
	v_fmac_f32_e32 v197, v75, v75
	v_fmac_f32_e32 v197, v76, v76
	v_fmac_f32_e32 v197, v77, v77
	global_load_dwordx4 v[218:221], v155, s[44:45] offset:512
	global_load_dwordx4 v[222:225], v155, s[44:45] offset:528
	s_waitcnt vmcnt(22)
	v_pk_add_f32 v[70:71], v[70:71], v[226:227]
	v_pk_add_f32 v[72:73], v[72:73], v[228:229]
	v_pk_add_f32 v[66:67], v[66:67], v[236:237]
	v_pk_add_f32 v[68:69], v[68:69], v[238:239]
	global_store_dwordx4 v157, v[70:73], s[98:99] offset:512
	global_store_dwordx4 v157, v[66:69], s[98:99] offset:528
	v_pk_mul_f32 v[226:227], v[86:87], v[70:71]
	v_pk_mul_f32 v[228:229], v[88:89], v[72:73]
	v_pk_mul_f32 v[236:237], v[82:83], v[66:67]
	v_pk_mul_f32 v[238:239], v[84:85], v[68:69]
	v_cvt_pk_bf16_f32 v192, v226, v227
	v_cvt_pk_bf16_f32 v193, v228, v229
	v_cvt_pk_bf16_f32 v194, v236, v237
	v_cvt_pk_bf16_f32 v195, v238, v239
	global_store_dwordx4 v203, v[192:195], s[46:47] offset:256
	v_fmac_f32_e32 v197, v70, v70
	v_fmac_f32_e32 v197, v71, v71
	v_fmac_f32_e32 v197, v72, v72
	v_fmac_f32_e32 v197, v73, v73
	v_fmac_f32_e32 v197, v66, v66
	v_fmac_f32_e32 v197, v67, v67
	v_fmac_f32_e32 v197, v68, v68
	v_fmac_f32_e32 v197, v69, v69
	v_mov_b32_e32 v198, v197
	s_nop 1
	v_permlane16_swap_b32_e32 v197, v198
	v_add_f32_e32 v197, v197, v198
	v_mov_b32_e32 v198, v197
	s_nop 1
	v_permlane32_swap_b32_e32 v197, v198
	v_add_f32_e32 v197, v197, v198
	v_add_u32_e32 v200, 0x1800, v201
	s_mov_b64 exec, s[38:39]
	global_store_dword v200, v197, s[50:51]
	s_mov_b64 exec, -1
	v_add_u32_e32 v156, 0x140000, v199
	global_load_dwordx4 v[226:229], v156, s[44:45]
	global_load_dwordx4 v[236:239], v156, s[44:45] offset:16
	s_waitcnt vmcnt(22)
	v_pk_add_f32 v[62:63], v[62:63], v[240:241]
	v_pk_add_f32 v[64:65], v[64:65], v[242:243]
	v_pk_add_f32 v[58:59], v[58:59], v[244:245]
	v_pk_add_f32 v[60:61], v[60:61], v[246:247]
	global_store_dwordx4 v154, v[62:65], s[98:99]
	global_store_dwordx4 v154, v[58:61], s[98:99] offset:16
	v_pk_mul_f32 v[240:241], v[102:103], v[62:63]
	v_pk_mul_f32 v[242:243], v[104:105], v[64:65]
	v_pk_mul_f32 v[244:245], v[98:99], v[58:59]
	v_pk_mul_f32 v[246:247], v[100:101], v[60:61]
	v_cvt_pk_bf16_f32 v188, v240, v241
	v_cvt_pk_bf16_f32 v189, v242, v243
	v_cvt_pk_bf16_f32 v190, v244, v245
	v_cvt_pk_bf16_f32 v191, v246, v247
	v_lshrrev_b32_e32 v202, 1, v154
	global_store_dwordx4 v202, v[188:191], s[46:47]
	v_mul_f32_e32 v196, v62, v62
	v_fmac_f32_e32 v196, v63, v63
	v_fmac_f32_e32 v196, v64, v64
	v_fmac_f32_e32 v196, v65, v65
	v_fmac_f32_e32 v196, v58, v58
	v_fmac_f32_e32 v196, v59, v59
	v_fmac_f32_e32 v196, v60, v60
	v_fmac_f32_e32 v196, v61, v61
	global_load_dwordx4 v[240:243], v156, s[44:45] offset:512
	global_load_dwordx4 v[244:247], v156, s[44:45] offset:528
	s_waitcnt vmcnt(22)
	v_pk_add_f32 v[54:55], v[54:55], v[180:181]
	v_pk_add_f32 v[56:57], v[56:57], v[182:183]
	v_pk_add_f32 v[50:51], v[50:51], v[184:185]
	v_pk_add_f32 v[52:53], v[52:53], v[186:187]
	global_store_dwordx4 v154, v[54:57], s[98:99] offset:512
	global_store_dwordx4 v154, v[50:53], s[98:99] offset:528
	v_pk_mul_f32 v[180:181], v[86:87], v[54:55]
	v_pk_mul_f32 v[182:183], v[88:89], v[56:57]
	v_pk_mul_f32 v[184:185], v[82:83], v[50:51]
	v_pk_mul_f32 v[186:187], v[84:85], v[52:53]
	v_cvt_pk_bf16_f32 v192, v180, v181
	v_cvt_pk_bf16_f32 v193, v182, v183
	v_cvt_pk_bf16_f32 v194, v184, v185
	v_cvt_pk_bf16_f32 v195, v186, v187
	global_store_dwordx4 v202, v[192:195], s[46:47] offset:256
	v_fmac_f32_e32 v196, v54, v54
	v_fmac_f32_e32 v196, v55, v55
	v_fmac_f32_e32 v196, v56, v56
	v_fmac_f32_e32 v196, v57, v57
	v_fmac_f32_e32 v196, v50, v50
	v_fmac_f32_e32 v196, v51, v51
	v_fmac_f32_e32 v196, v52, v52
	v_fmac_f32_e32 v196, v53, v53
	v_mov_b32_e32 v198, v196
	s_nop 1
	v_permlane16_swap_b32_e32 v196, v198
	v_add_f32_e32 v196, v196, v198
	v_mov_b32_e32 v198, v196
	s_nop 1
	v_permlane32_swap_b32_e32 v196, v198
	v_add_f32_e32 v196, v196, v198
	v_add_u32_e32 v200, 0x4000, v201
	s_mov_b64 exec, s[38:39]
	global_store_dword v200, v196, s[50:51]
	s_mov_b64 exec, -1
	v_add_u32_e32 v157, 0x160000, v199
	global_load_dwordx4 v[180:183], v157, s[44:45]
	global_load_dwordx4 v[184:187], v157, s[44:45] offset:16
	s_waitcnt vmcnt(22)
	v_pk_add_f32 v[46:47], v[46:47], v[210:211]
	v_pk_add_f32 v[48:49], v[48:49], v[212:213]
	v_pk_add_f32 v[42:43], v[42:43], v[214:215]
	v_pk_add_f32 v[44:45], v[44:45], v[216:217]
	global_store_dwordx4 v155, v[46:49], s[98:99]
	global_store_dwordx4 v155, v[42:45], s[98:99] offset:16
	v_pk_mul_f32 v[210:211], v[102:103], v[46:47]
	v_pk_mul_f32 v[212:213], v[104:105], v[48:49]
	v_pk_mul_f32 v[214:215], v[98:99], v[42:43]
	v_pk_mul_f32 v[216:217], v[100:101], v[44:45]
	v_cvt_pk_bf16_f32 v188, v210, v211
	v_cvt_pk_bf16_f32 v189, v212, v213
	v_cvt_pk_bf16_f32 v190, v214, v215
	v_cvt_pk_bf16_f32 v191, v216, v217
	v_lshrrev_b32_e32 v203, 1, v155
	global_store_dwordx4 v203, v[188:191], s[46:47]
	v_mul_f32_e32 v197, v46, v46
	v_fmac_f32_e32 v197, v47, v47
	v_fmac_f32_e32 v197, v48, v48
	v_fmac_f32_e32 v197, v49, v49
	v_fmac_f32_e32 v197, v42, v42
	v_fmac_f32_e32 v197, v43, v43
	v_fmac_f32_e32 v197, v44, v44
	v_fmac_f32_e32 v197, v45, v45
	global_load_dwordx4 v[210:213], v157, s[44:45] offset:512
	global_load_dwordx4 v[214:217], v157, s[44:45] offset:528
	s_waitcnt vmcnt(22)
	v_pk_add_f32 v[38:39], v[38:39], v[218:219]
	v_pk_add_f32 v[40:41], v[40:41], v[220:221]
	v_pk_add_f32 v[34:35], v[34:35], v[222:223]
	v_pk_add_f32 v[36:37], v[36:37], v[224:225]
	global_store_dwordx4 v155, v[38:41], s[98:99] offset:512
	global_store_dwordx4 v155, v[34:37], s[98:99] offset:528
	v_pk_mul_f32 v[218:219], v[86:87], v[38:39]
	v_pk_mul_f32 v[220:221], v[88:89], v[40:41]
	v_pk_mul_f32 v[222:223], v[82:83], v[34:35]
	v_pk_mul_f32 v[224:225], v[84:85], v[36:37]
	v_cvt_pk_bf16_f32 v192, v218, v219
	v_cvt_pk_bf16_f32 v193, v220, v221
	v_cvt_pk_bf16_f32 v194, v222, v223
	v_cvt_pk_bf16_f32 v195, v224, v225
	global_store_dwordx4 v203, v[192:195], s[46:47] offset:256
	v_fmac_f32_e32 v197, v38, v38
	v_fmac_f32_e32 v197, v39, v39
	v_fmac_f32_e32 v197, v40, v40
	v_fmac_f32_e32 v197, v41, v41
	v_fmac_f32_e32 v197, v34, v34
	v_fmac_f32_e32 v197, v35, v35
	v_fmac_f32_e32 v197, v36, v36
	v_fmac_f32_e32 v197, v37, v37
	v_mov_b32_e32 v198, v197
	s_nop 1
	v_permlane16_swap_b32_e32 v197, v198
	v_add_f32_e32 v197, v197, v198
	v_mov_b32_e32 v198, v197
	s_nop 1
	v_permlane32_swap_b32_e32 v197, v198
	v_add_f32_e32 v197, v197, v198
	v_add_u32_e32 v200, 0x4800, v201
	s_mov_b64 exec, s[38:39]
	global_store_dword v200, v197, s[50:51]
	s_mov_b64 exec, -1
	s_waitcnt vmcnt(20)
	v_pk_add_f32 v[30:31], v[30:31], v[226:227]
	v_pk_add_f32 v[32:33], v[32:33], v[228:229]
	v_pk_add_f32 v[26:27], v[26:27], v[236:237]
	v_pk_add_f32 v[28:29], v[28:29], v[238:239]
	global_store_dwordx4 v156, v[30:33], s[98:99]
	global_store_dwordx4 v156, v[26:29], s[98:99] offset:16
	v_pk_mul_f32 v[226:227], v[102:103], v[30:31]
	v_pk_mul_f32 v[228:229], v[104:105], v[32:33]
	v_pk_mul_f32 v[236:237], v[98:99], v[26:27]
	v_pk_mul_f32 v[238:239], v[100:101], v[28:29]
	v_cvt_pk_bf16_f32 v188, v226, v227
	v_cvt_pk_bf16_f32 v189, v228, v229
	v_cvt_pk_bf16_f32 v190, v236, v237
	v_cvt_pk_bf16_f32 v191, v238, v239
	v_lshrrev_b32_e32 v202, 1, v156
	global_store_dwordx4 v202, v[188:191], s[46:47]
	v_mul_f32_e32 v196, v30, v30
	v_fmac_f32_e32 v196, v31, v31
	v_fmac_f32_e32 v196, v32, v32
	v_fmac_f32_e32 v196, v33, v33
	v_fmac_f32_e32 v196, v26, v26
	v_fmac_f32_e32 v196, v27, v27
	v_fmac_f32_e32 v196, v28, v28
	v_fmac_f32_e32 v196, v29, v29
	s_waitcnt vmcnt(18)
	v_pk_add_f32 v[22:23], v[22:23], v[240:241]
	v_pk_add_f32 v[24:25], v[24:25], v[242:243]
	v_pk_add_f32 v[18:19], v[18:19], v[244:245]
	v_pk_add_f32 v[20:21], v[20:21], v[246:247]
	global_store_dwordx4 v156, v[22:25], s[98:99] offset:512
	global_store_dwordx4 v156, v[18:21], s[98:99] offset:528
	v_pk_mul_f32 v[240:241], v[86:87], v[22:23]
	v_pk_mul_f32 v[242:243], v[88:89], v[24:25]
	v_pk_mul_f32 v[244:245], v[82:83], v[18:19]
	v_pk_mul_f32 v[246:247], v[84:85], v[20:21]
	v_cvt_pk_bf16_f32 v192, v240, v241
	v_cvt_pk_bf16_f32 v193, v242, v243
	v_cvt_pk_bf16_f32 v194, v244, v245
	v_cvt_pk_bf16_f32 v195, v246, v247
	global_store_dwordx4 v202, v[192:195], s[46:47] offset:256
	v_fmac_f32_e32 v196, v22, v22
	v_fmac_f32_e32 v196, v23, v23
	v_fmac_f32_e32 v196, v24, v24
	v_fmac_f32_e32 v196, v25, v25
	v_fmac_f32_e32 v196, v18, v18
	v_fmac_f32_e32 v196, v19, v19
	v_fmac_f32_e32 v196, v20, v20
	v_fmac_f32_e32 v196, v21, v21
	v_mov_b32_e32 v198, v196
	s_nop 1
	v_permlane16_swap_b32_e32 v196, v198
	v_add_f32_e32 v196, v196, v198
	v_mov_b32_e32 v198, v196
	s_nop 1
	v_permlane32_swap_b32_e32 v196, v198
	v_add_f32_e32 v196, v196, v198
	v_add_u32_e32 v200, 0x5000, v201
	s_mov_b64 exec, s[38:39]
	global_store_dword v200, v196, s[50:51]
	s_mov_b64 exec, -1
	s_waitcnt vmcnt(16)
	v_pk_add_f32 v[14:15], v[14:15], v[180:181]
	v_pk_add_f32 v[16:17], v[16:17], v[182:183]
	v_pk_add_f32 v[10:11], v[10:11], v[184:185]
	v_pk_add_f32 v[12:13], v[12:13], v[186:187]
	global_store_dwordx4 v157, v[14:17], s[98:99]
	global_store_dwordx4 v157, v[10:13], s[98:99] offset:16
	v_pk_mul_f32 v[180:181], v[102:103], v[14:15]
	v_pk_mul_f32 v[182:183], v[104:105], v[16:17]
	v_pk_mul_f32 v[184:185], v[98:99], v[10:11]
	v_pk_mul_f32 v[186:187], v[100:101], v[12:13]
	v_cvt_pk_bf16_f32 v188, v180, v181
	v_cvt_pk_bf16_f32 v189, v182, v183
	v_cvt_pk_bf16_f32 v190, v184, v185
	v_cvt_pk_bf16_f32 v191, v186, v187
	v_lshrrev_b32_e32 v203, 1, v157
	global_store_dwordx4 v203, v[188:191], s[46:47]
	v_mul_f32_e32 v197, v14, v14
	v_fmac_f32_e32 v197, v15, v15
	v_fmac_f32_e32 v197, v16, v16
	v_fmac_f32_e32 v197, v17, v17
	v_fmac_f32_e32 v197, v10, v10
	v_fmac_f32_e32 v197, v11, v11
	v_fmac_f32_e32 v197, v12, v12
	v_fmac_f32_e32 v197, v13, v13
	s_waitcnt vmcnt(14)
	v_pk_add_f32 v[6:7], v[6:7], v[210:211]
	v_pk_add_f32 v[8:9], v[8:9], v[212:213]
	v_pk_add_f32 v[2:3], v[2:3], v[214:215]
	v_pk_add_f32 v[4:5], v[4:5], v[216:217]
	global_store_dwordx4 v157, v[6:9], s[98:99] offset:512
	global_store_dwordx4 v157, v[2:5], s[98:99] offset:528
	v_pk_mul_f32 v[210:211], v[86:87], v[6:7]
	v_pk_mul_f32 v[212:213], v[88:89], v[8:9]
	v_pk_mul_f32 v[214:215], v[82:83], v[2:3]
	v_pk_mul_f32 v[216:217], v[84:85], v[4:5]
	v_cvt_pk_bf16_f32 v192, v210, v211
	v_cvt_pk_bf16_f32 v193, v212, v213
	v_cvt_pk_bf16_f32 v194, v214, v215
	v_cvt_pk_bf16_f32 v195, v216, v217
	global_store_dwordx4 v203, v[192:195], s[46:47] offset:256
	v_fmac_f32_e32 v197, v6, v6
	v_fmac_f32_e32 v197, v7, v7
	v_fmac_f32_e32 v197, v8, v8
	v_fmac_f32_e32 v197, v9, v9
	v_fmac_f32_e32 v197, v2, v2
	v_fmac_f32_e32 v197, v3, v3
	v_fmac_f32_e32 v197, v4, v4
	v_fmac_f32_e32 v197, v5, v5
	v_mov_b32_e32 v198, v197
	s_nop 1
	v_permlane16_swap_b32_e32 v197, v198
	v_add_f32_e32 v197, v197, v198
	v_mov_b32_e32 v198, v197
	s_nop 1
	v_permlane32_swap_b32_e32 v197, v198
	v_add_f32_e32 v197, v197, v198
	v_add_u32_e32 v200, 0x5800, v201
	s_mov_b64 exec, s[38:39]
	global_store_dword v200, v197, s[50:51]
	s_mov_b64 exec, -1

.LBB0_731:
	v_readlane_b32 s18, v253, 4
	v_readlane_b32 s19, v253, 5
	s_load_dwordx2 s[22:23], s[18:19], 0x98
	v_lshl_add_u32 v170, s5, 8, v149
	s_load_dwordx2 s[18:19], s[18:19], s58 offset:0x0
	v_lshl_or_b32 v168, s4, 8, v177
	v_lshlrev_b32_e32 v199, 11, v170
	v_add_lshl_u32 v199, v199, v168, 2
	v_lshlrev_b32_e32 v200, 2, v168
	v_lshlrev_b32_e32 v201, 7, v170
	s_waitcnt lgkmcnt(0)
	s_add_u32 s48, s22, 0x9f00000
	s_addc_u32 s49, s23, 0
	s_add_u32 s46, s22, 0xdf00000
	s_addc_u32 s47, s23, 0
	s_add_u32 s18, s18, s57
	s_addc_u32 s19, s19, 0
	s_lshl_b32 s4, s4, 2
	s_ashr_i32 s5, s4, 31
	s_lshl_b64 s[4:5], s[4:5], 2
	s_add_u32 s4, s22, s4
	s_addc_u32 s5, s23, s5
	s_add_u32 s4, s4, s59
	s_addc_u32 s5, s5, 0
	s_add_u32 s22, s4, 0x1a700000
	s_addc_u32 s23, s5, 0
	global_load_dwordx4 v[54:57], v200, s[18:19]
	global_load_dwordx4 v[50:53], v200, s[18:19] offset:16
	global_load_dwordx4 v[46:49], v200, s[18:19] offset:512
	global_load_dwordx4 v[42:45], v200, s[18:19] offset:528
	s_andn2_b64 vcc, exec, s[6:7]
	s_cbranch_vccnz .Lres_h_nocopy
	v_mov_b32_e32 v154, v199
	global_load_dwordx4 v[210:213], v154, s[48:49]
	global_load_dwordx4 v[214:217], v154, s[48:49] offset:16
	global_load_dwordx4 v[218:221], v154, s[48:49] offset:512
	global_load_dwordx4 v[222:225], v154, s[48:49] offset:528
	v_add_u32_e32 v155, 0x20000, v199
	global_load_dwordx4 v[226:229], v155, s[48:49]
	global_load_dwordx4 v[236:239], v155, s[48:49] offset:16
	global_load_dwordx4 v[240:243], v155, s[48:49] offset:512
	global_load_dwordx4 v[244:247], v155, s[48:49] offset:528
	v_add_u32_e32 v156, 0x40000, v199
	global_load_dwordx4 v[180:183], v156, s[48:49]
	global_load_dwordx4 v[184:187], v156, s[48:49] offset:16
	s_waitcnt vmcnt(8)
	v_pk_add_f32 v[142:143], v[142:143], v[210:211]
	v_pk_add_f32 v[144:145], v[144:145], v[212:213]
	v_pk_add_f32 v[138:139], v[138:139], v[214:215]
	v_pk_add_f32 v[140:141], v[140:141], v[216:217]
	global_store_dwordx4 v154, v[142:145], s[48:49]
	global_store_dwordx4 v154, v[138:141], s[48:49] offset:16
	v_pk_mul_f32 v[210:211], v[54:55], v[142:143]
	v_pk_mul_f32 v[212:213], v[56:57], v[144:145]
	v_pk_mul_f32 v[214:215], v[50:51], v[138:139]
	v_pk_mul_f32 v[216:217], v[52:53], v[140:141]
	v_cvt_pk_bf16_f32 v188, v210, v211
	v_cvt_pk_bf16_f32 v189, v212, v213
	v_cvt_pk_bf16_f32 v190, v214, v215
	v_cvt_pk_bf16_f32 v191, v216, v217
	v_lshrrev_b32_e32 v202, 1, v154
	global_store_dwordx4 v202, v[188:191], s[46:47]
	v_mul_f32_e32 v196, v142, v142
	v_fmac_f32_e32 v196, v143, v143
	v_fmac_f32_e32 v196, v144, v144
	v_fmac_f32_e32 v196, v145, v145
	v_fmac_f32_e32 v196, v138, v138
	v_fmac_f32_e32 v196, v139, v139
	v_fmac_f32_e32 v196, v140, v140
	v_fmac_f32_e32 v196, v141, v141
	global_load_dwordx4 v[210:213], v156, s[48:49] offset:512
	global_load_dwordx4 v[214:217], v156, s[48:49] offset:528
	s_waitcnt vmcnt(11)
	v_pk_add_f32 v[134:135], v[134:135], v[218:219]
	v_pk_add_f32 v[136:137], v[136:137], v[220:221]
	v_pk_add_f32 v[130:131], v[130:131], v[222:223]
	v_pk_add_f32 v[132:133], v[132:133], v[224:225]
	global_store_dwordx4 v154, v[134:137], s[48:49] offset:512
	global_store_dwordx4 v154, v[130:133], s[48:49] offset:528
	v_pk_mul_f32 v[218:219], v[46:47], v[134:135]
	v_pk_mul_f32 v[220:221], v[48:49], v[136:137]
	v_pk_mul_f32 v[222:223], v[42:43], v[130:131]
	v_pk_mul_f32 v[224:225], v[44:45], v[132:133]
	v_cvt_pk_bf16_f32 v192, v218, v219
	v_cvt_pk_bf16_f32 v193, v220, v221
	v_cvt_pk_bf16_f32 v194, v222, v223
	v_cvt_pk_bf16_f32 v195, v224, v225
	global_store_dwordx4 v202, v[192:195], s[46:47] offset:256
	v_fmac_f32_e32 v196, v134, v134
	v_fmac_f32_e32 v196, v135, v135
	v_fmac_f32_e32 v196, v136, v136
	v_fmac_f32_e32 v196, v137, v137
	v_fmac_f32_e32 v196, v130, v130
	v_fmac_f32_e32 v196, v131, v131
	v_fmac_f32_e32 v196, v132, v132
	v_fmac_f32_e32 v196, v133, v133
	v_mov_b32_e32 v198, v196
	s_nop 1
	v_permlane16_swap_b32_e32 v196, v198
	v_add_f32_e32 v196, v196, v198
	v_mov_b32_e32 v198, v196
	s_nop 1
	v_permlane32_swap_b32_e32 v196, v198
	v_add_f32_e32 v196, v196, v198
	v_mov_b32_e32 v200, v201
	s_mov_b64 exec, s[38:39]
	global_store_dword v200, v196, s[22:23]
	s_mov_b64 exec, -1
	v_add_u32_e32 v157, 0x60000, v199
	global_load_dwordx4 v[218:221], v157, s[48:49]
	global_load_dwordx4 v[222:225], v157, s[48:49] offset:16
	s_waitcnt vmcnt(15)
	v_pk_add_f32 v[126:127], v[126:127], v[226:227]
	v_pk_add_f32 v[128:129], v[128:129], v[228:229]
	v_pk_add_f32 v[122:123], v[122:123], v[236:237]
	v_pk_add_f32 v[124:125], v[124:125], v[238:239]
	global_store_dwordx4 v155, v[126:129], s[48:49]
	global_store_dwordx4 v155, v[122:125], s[48:49] offset:16
	v_pk_mul_f32 v[226:227], v[54:55], v[126:127]
	v_pk_mul_f32 v[228:229], v[56:57], v[128:129]
	v_pk_mul_f32 v[236:237], v[50:51], v[122:123]
	v_pk_mul_f32 v[238:239], v[52:53], v[124:125]
	v_cvt_pk_bf16_f32 v188, v226, v227
	v_cvt_pk_bf16_f32 v189, v228, v229
	v_cvt_pk_bf16_f32 v190, v236, v237
	v_cvt_pk_bf16_f32 v191, v238, v239
	v_lshrrev_b32_e32 v203, 1, v155
	global_store_dwordx4 v203, v[188:191], s[46:47]
	v_mul_f32_e32 v197, v126, v126
	v_fmac_f32_e32 v197, v127, v127
	v_fmac_f32_e32 v197, v128, v128
	v_fmac_f32_e32 v197, v129, v129
	v_fmac_f32_e32 v197, v122, v122
	v_fmac_f32_e32 v197, v123, v123
	v_fmac_f32_e32 v197, v124, v124
	v_fmac_f32_e32 v197, v125, v125
	global_load_dwordx4 v[226:229], v157, s[48:49] offset:512
	global_load_dwordx4 v[236:239], v157, s[48:49] offset:528
	s_waitcnt vmcnt(18)
	v_pk_add_f32 v[118:119], v[118:119], v[240:241]
	v_pk_add_f32 v[120:121], v[120:121], v[242:243]
	v_pk_add_f32 v[114:115], v[114:115], v[244:245]
	v_pk_add_f32 v[116:117], v[116:117], v[246:247]
	global_store_dwordx4 v155, v[118:121], s[48:49] offset:512
	global_store_dwordx4 v155, v[114:117], s[48:49] offset:528
	v_pk_mul_f32 v[240:241], v[46:47], v[118:119]
	v_pk_mul_f32 v[242:243], v[48:49], v[120:121]
	v_pk_mul_f32 v[244:245], v[42:43], v[114:115]
	v_pk_mul_f32 v[246:247], v[44:45], v[116:117]
	v_cvt_pk_bf16_f32 v192, v240, v241
	v_cvt_pk_bf16_f32 v193, v242, v243
	v_cvt_pk_bf16_f32 v194, v244, v245
	v_cvt_pk_bf16_f32 v195, v246, v247
	global_store_dwordx4 v203, v[192:195], s[46:47] offset:256
	v_fmac_f32_e32 v197, v118, v118
	v_fmac_f32_e32 v197, v119, v119
	v_fmac_f32_e32 v197, v120, v120
	v_fmac_f32_e32 v197, v121, v121
	v_fmac_f32_e32 v197, v114, v114
	v_fmac_f32_e32 v197, v115, v115
	v_fmac_f32_e32 v197, v116, v116
	v_fmac_f32_e32 v197, v117, v117
	v_mov_b32_e32 v198, v197
	s_nop 1
	v_permlane16_swap_b32_e32 v197, v198
	v_add_f32_e32 v197, v197, v198
	v_mov_b32_e32 v198, v197
	s_nop 1
	v_permlane32_swap_b32_e32 v197, v198
	v_add_f32_e32 v197, v197, v198
	v_add_u32_e32 v200, 0x800, v201
	s_mov_b64 exec, s[38:39]
	global_store_dword v200, v197, s[22:23]
	s_mov_b64 exec, -1
	v_add_u32_e32 v154, 0x100000, v199
	global_load_dwordx4 v[240:243], v154, s[48:49]
	global_load_dwordx4 v[244:247], v154, s[48:49] offset:16
	s_waitcnt vmcnt(22)
	v_pk_add_f32 v[110:111], v[110:111], v[180:181]
	v_pk_add_f32 v[112:113], v[112:113], v[182:183]
	v_pk_add_f32 v[106:107], v[106:107], v[184:185]
	v_pk_add_f32 v[108:109], v[108:109], v[186:187]
	global_store_dwordx4 v156, v[110:113], s[48:49]
	global_store_dwordx4 v156, v[106:109], s[48:49] offset:16
	v_pk_mul_f32 v[180:181], v[54:55], v[110:111]
	v_pk_mul_f32 v[182:183], v[56:57], v[112:113]
	v_pk_mul_f32 v[184:185], v[50:51], v[106:107]
	v_pk_mul_f32 v[186:187], v[52:53], v[108:109]
	v_cvt_pk_bf16_f32 v188, v180, v181
	v_cvt_pk_bf16_f32 v189, v182, v183
	v_cvt_pk_bf16_f32 v190, v184, v185
	v_cvt_pk_bf16_f32 v191, v186, v187
	v_lshrrev_b32_e32 v202, 1, v156
	global_store_dwordx4 v202, v[188:191], s[46:47]
	v_mul_f32_e32 v196, v110, v110
	v_fmac_f32_e32 v196, v111, v111
	v_fmac_f32_e32 v196, v112, v112
	v_fmac_f32_e32 v196, v113, v113
	v_fmac_f32_e32 v196, v106, v106
	v_fmac_f32_e32 v196, v107, v107
	v_fmac_f32_e32 v196, v108, v108
	v_fmac_f32_e32 v196, v109, v109
	global_load_dwordx4 v[180:183], v154, s[48:49] offset:512
	global_load_dwordx4 v[184:187], v154, s[48:49] offset:528
	s_waitcnt vmcnt(22)
	v_pk_add_f32 v[102:103], v[102:103], v[210:211]
	v_pk_add_f32 v[104:105], v[104:105], v[212:213]
	v_pk_add_f32 v[98:99], v[98:99], v[214:215]
	v_pk_add_f32 v[100:101], v[100:101], v[216:217]
	global_store_dwordx4 v156, v[102:105], s[48:49] offset:512
	global_store_dwordx4 v156, v[98:101], s[48:49] offset:528
	v_pk_mul_f32 v[210:211], v[46:47], v[102:103]
	v_pk_mul_f32 v[212:213], v[48:49], v[104:105]
	v_pk_mul_f32 v[214:215], v[42:43], v[98:99]
	v_pk_mul_f32 v[216:217], v[44:45], v[100:101]
	v_cvt_pk_bf16_f32 v192, v210, v211
	v_cvt_pk_bf16_f32 v193, v212, v213
	v_cvt_pk_bf16_f32 v194, v214, v215
	v_cvt_pk_bf16_f32 v195, v216, v217
	global_store_dwordx4 v202, v[192:195], s[46:47] offset:256
	v_fmac_f32_e32 v196, v102, v102
	v_fmac_f32_e32 v196, v103, v103
	v_fmac_f32_e32 v196, v104, v104
	v_fmac_f32_e32 v196, v105, v105
	v_fmac_f32_e32 v196, v98, v98
	v_fmac_f32_e32 v196, v99, v99
	v_fmac_f32_e32 v196, v100, v100
	v_fmac_f32_e32 v196, v101, v101
	v_mov_b32_e32 v198, v196
	s_nop 1
	v_permlane16_swap_b32_e32 v196, v198
	v_add_f32_e32 v196, v196, v198
	v_mov_b32_e32 v198, v196
	s_nop 1
	v_permlane32_swap_b32_e32 v196, v198
	v_add_f32_e32 v196, v196, v198
	v_add_u32_e32 v200, 0x1000, v201
	s_mov_b64 exec, s[38:39]
	global_store_dword v200, v196, s[22:23]
	s_mov_b64 exec, -1
	v_add_u32_e32 v155, 0x120000, v199
	global_load_dwordx4 v[210:213], v155, s[48:49]
	global_load_dwordx4 v[214:217], v155, s[48:49] offset:16
	s_waitcnt vmcnt(22)
	v_pk_add_f32 v[94:95], v[94:95], v[218:219]
	v_pk_add_f32 v[96:97], v[96:97], v[220:221]
	v_pk_add_f32 v[90:91], v[90:91], v[222:223]
	v_pk_add_f32 v[92:93], v[92:93], v[224:225]
	global_store_dwordx4 v157, v[94:97], s[48:49]
	global_store_dwordx4 v157, v[90:93], s[48:49] offset:16
	v_pk_mul_f32 v[218:219], v[54:55], v[94:95]
	v_pk_mul_f32 v[220:221], v[56:57], v[96:97]
	v_pk_mul_f32 v[222:223], v[50:51], v[90:91]
	v_pk_mul_f32 v[224:225], v[52:53], v[92:93]
	v_cvt_pk_bf16_f32 v188, v218, v219
	v_cvt_pk_bf16_f32 v189, v220, v221
	v_cvt_pk_bf16_f32 v190, v222, v223
	v_cvt_pk_bf16_f32 v191, v224, v225
	v_lshrrev_b32_e32 v203, 1, v157
	global_store_dwordx4 v203, v[188:191], s[46:47]
	v_mul_f32_e32 v197, v94, v94
	v_fmac_f32_e32 v197, v95, v95
	v_fmac_f32_e32 v197, v96, v96
	v_fmac_f32_e32 v197, v97, v97
	v_fmac_f32_e32 v197, v90, v90
	v_fmac_f32_e32 v197, v91, v91
	v_fmac_f32_e32 v197, v92, v92
	v_fmac_f32_e32 v197, v93, v93
	global_load_dwordx4 v[218:221], v155, s[48:49] offset:512
	global_load_dwordx4 v[222:225], v155, s[48:49] offset:528
	s_waitcnt vmcnt(22)
	v_pk_add_f32 v[86:87], v[86:87], v[226:227]
	v_pk_add_f32 v[88:89], v[88:89], v[228:229]
	v_pk_add_f32 v[82:83], v[82:83], v[236:237]
	v_pk_add_f32 v[84:85], v[84:85], v[238:239]
	global_store_dwordx4 v157, v[86:89], s[48:49] offset:512
	global_store_dwordx4 v157, v[82:85], s[48:49] offset:528
	v_pk_mul_f32 v[226:227], v[46:47], v[86:87]
	v_pk_mul_f32 v[228:229], v[48:49], v[88:89]
	v_pk_mul_f32 v[236:237], v[42:43], v[82:83]
	v_pk_mul_f32 v[238:239], v[44:45], v[84:85]
	v_cvt_pk_bf16_f32 v192, v226, v227
	v_cvt_pk_bf16_f32 v193, v228, v229
	v_cvt_pk_bf16_f32 v194, v236, v237
	v_cvt_pk_bf16_f32 v195, v238, v239
	global_store_dwordx4 v203, v[192:195], s[46:47] offset:256
	v_fmac_f32_e32 v197, v86, v86
	v_fmac_f32_e32 v197, v87, v87
	v_fmac_f32_e32 v197, v88, v88
	v_fmac_f32_e32 v197, v89, v89
	v_fmac_f32_e32 v197, v82, v82
	v_fmac_f32_e32 v197, v83, v83
	v_fmac_f32_e32 v197, v84, v84
	v_fmac_f32_e32 v197, v85, v85
	v_mov_b32_e32 v198, v197
	s_nop 1
	v_permlane16_swap_b32_e32 v197, v198
	v_add_f32_e32 v197, v197, v198
	v_mov_b32_e32 v198, v197
	s_nop 1
	v_permlane32_swap_b32_e32 v197, v198
	v_add_f32_e32 v197, v197, v198
	v_add_u32_e32 v200, 0x1800, v201
	s_mov_b64 exec, s[38:39]
	global_store_dword v200, v197, s[22:23]
	s_mov_b64 exec, -1
	v_add_u32_e32 v156, 0x140000, v199
	global_load_dwordx4 v[226:229], v156, s[48:49]
	global_load_dwordx4 v[236:239], v156, s[48:49] offset:16
	s_waitcnt vmcnt(22)
	v_pk_add_f32 v[78:79], v[78:79], v[240:241]
	v_pk_add_f32 v[80:81], v[80:81], v[242:243]
	v_pk_add_f32 v[74:75], v[74:75], v[244:245]
	v_pk_add_f32 v[76:77], v[76:77], v[246:247]
	global_store_dwordx4 v154, v[78:81], s[48:49]
	global_store_dwordx4 v154, v[74:77], s[48:49] offset:16
	v_pk_mul_f32 v[240:241], v[54:55], v[78:79]
	v_pk_mul_f32 v[242:243], v[56:57], v[80:81]
	v_pk_mul_f32 v[244:245], v[50:51], v[74:75]
	v_pk_mul_f32 v[246:247], v[52:53], v[76:77]
	v_cvt_pk_bf16_f32 v188, v240, v241
	v_cvt_pk_bf16_f32 v189, v242, v243
	v_cvt_pk_bf16_f32 v190, v244, v245
	v_cvt_pk_bf16_f32 v191, v246, v247
	v_lshrrev_b32_e32 v202, 1, v154
	global_store_dwordx4 v202, v[188:191], s[46:47]
	v_mul_f32_e32 v196, v78, v78
	v_fmac_f32_e32 v196, v79, v79
	v_fmac_f32_e32 v196, v80, v80
	v_fmac_f32_e32 v196, v81, v81
	v_fmac_f32_e32 v196, v74, v74
	v_fmac_f32_e32 v196, v75, v75
	v_fmac_f32_e32 v196, v76, v76
	v_fmac_f32_e32 v196, v77, v77
	global_load_dwordx4 v[240:243], v156, s[48:49] offset:512
	global_load_dwordx4 v[244:247], v156, s[48:49] offset:528
	s_waitcnt vmcnt(22)
	v_pk_add_f32 v[70:71], v[70:71], v[180:181]
	v_pk_add_f32 v[72:73], v[72:73], v[182:183]
	v_pk_add_f32 v[66:67], v[66:67], v[184:185]
	v_pk_add_f32 v[68:69], v[68:69], v[186:187]
	global_store_dwordx4 v154, v[70:73], s[48:49] offset:512
	global_store_dwordx4 v154, v[66:69], s[48:49] offset:528
	v_pk_mul_f32 v[180:181], v[46:47], v[70:71]
	v_pk_mul_f32 v[182:183], v[48:49], v[72:73]
	v_pk_mul_f32 v[184:185], v[42:43], v[66:67]
	v_pk_mul_f32 v[186:187], v[44:45], v[68:69]
	v_cvt_pk_bf16_f32 v192, v180, v181
	v_cvt_pk_bf16_f32 v193, v182, v183
	v_cvt_pk_bf16_f32 v194, v184, v185
	v_cvt_pk_bf16_f32 v195, v186, v187
	global_store_dwordx4 v202, v[192:195], s[46:47] offset:256
	v_fmac_f32_e32 v196, v70, v70
	v_fmac_f32_e32 v196, v71, v71
	v_fmac_f32_e32 v196, v72, v72
	v_fmac_f32_e32 v196, v73, v73
	v_fmac_f32_e32 v196, v66, v66
	v_fmac_f32_e32 v196, v67, v67
	v_fmac_f32_e32 v196, v68, v68
	v_fmac_f32_e32 v196, v69, v69
	v_mov_b32_e32 v198, v196
	s_nop 1
	v_permlane16_swap_b32_e32 v196, v198
	v_add_f32_e32 v196, v196, v198
	v_mov_b32_e32 v198, v196
	s_nop 1
	v_permlane32_swap_b32_e32 v196, v198
	v_add_f32_e32 v196, v196, v198
	v_add_u32_e32 v200, 0x4000, v201
	s_mov_b64 exec, s[38:39]
	global_store_dword v200, v196, s[22:23]
	s_mov_b64 exec, -1
	v_add_u32_e32 v157, 0x160000, v199
	global_load_dwordx4 v[180:183], v157, s[48:49]
	global_load_dwordx4 v[184:187], v157, s[48:49] offset:16
	s_waitcnt vmcnt(22)
	v_pk_add_f32 v[62:63], v[62:63], v[210:211]
	v_pk_add_f32 v[64:65], v[64:65], v[212:213]
	v_pk_add_f32 v[58:59], v[58:59], v[214:215]
	v_pk_add_f32 v[60:61], v[60:61], v[216:217]
	global_store_dwordx4 v155, v[62:65], s[48:49]
	global_store_dwordx4 v155, v[58:61], s[48:49] offset:16
	v_pk_mul_f32 v[210:211], v[54:55], v[62:63]
	v_pk_mul_f32 v[212:213], v[56:57], v[64:65]
	v_pk_mul_f32 v[214:215], v[50:51], v[58:59]
	v_pk_mul_f32 v[216:217], v[52:53], v[60:61]
	v_cvt_pk_bf16_f32 v188, v210, v211
	v_cvt_pk_bf16_f32 v189, v212, v213
	v_cvt_pk_bf16_f32 v190, v214, v215
	v_cvt_pk_bf16_f32 v191, v216, v217
	v_lshrrev_b32_e32 v203, 1, v155
	global_store_dwordx4 v203, v[188:191], s[46:47]
	v_mul_f32_e32 v197, v62, v62
	v_fmac_f32_e32 v197, v63, v63
	v_fmac_f32_e32 v197, v64, v64
	v_fmac_f32_e32 v197, v65, v65
	v_fmac_f32_e32 v197, v58, v58
	v_fmac_f32_e32 v197, v59, v59
	v_fmac_f32_e32 v197, v60, v60
	v_fmac_f32_e32 v197, v61, v61
	global_load_dwordx4 v[210:213], v157, s[48:49] offset:512
	global_load_dwordx4 v[214:217], v157, s[48:49] offset:528
	s_waitcnt vmcnt(22)
	v_pk_add_f32 v[38:39], v[38:39], v[218:219]
	v_pk_add_f32 v[40:41], v[40:41], v[220:221]
	v_pk_add_f32 v[34:35], v[34:35], v[222:223]
	v_pk_add_f32 v[36:37], v[36:37], v[224:225]
	global_store_dwordx4 v155, v[38:41], s[48:49] offset:512
	global_store_dwordx4 v155, v[34:37], s[48:49] offset:528
	v_pk_mul_f32 v[218:219], v[46:47], v[38:39]
	v_pk_mul_f32 v[220:221], v[48:49], v[40:41]
	v_pk_mul_f32 v[222:223], v[42:43], v[34:35]
	v_pk_mul_f32 v[224:225], v[44:45], v[36:37]
	v_cvt_pk_bf16_f32 v192, v218, v219
	v_cvt_pk_bf16_f32 v193, v220, v221
	v_cvt_pk_bf16_f32 v194, v222, v223
	v_cvt_pk_bf16_f32 v195, v224, v225
	global_store_dwordx4 v203, v[192:195], s[46:47] offset:256
	v_fmac_f32_e32 v197, v38, v38
	v_fmac_f32_e32 v197, v39, v39
	v_fmac_f32_e32 v197, v40, v40
	v_fmac_f32_e32 v197, v41, v41
	v_fmac_f32_e32 v197, v34, v34
	v_fmac_f32_e32 v197, v35, v35
	v_fmac_f32_e32 v197, v36, v36
	v_fmac_f32_e32 v197, v37, v37
	v_mov_b32_e32 v198, v197
	s_nop 1
	v_permlane16_swap_b32_e32 v197, v198
	v_add_f32_e32 v197, v197, v198
	v_mov_b32_e32 v198, v197
	s_nop 1
	v_permlane32_swap_b32_e32 v197, v198
	v_add_f32_e32 v197, v197, v198
	v_add_u32_e32 v200, 0x4800, v201
	s_mov_b64 exec, s[38:39]
	global_store_dword v200, v197, s[22:23]
	s_mov_b64 exec, -1
	s_waitcnt vmcnt(20)
	v_pk_add_f32 v[30:31], v[30:31], v[226:227]
	v_pk_add_f32 v[32:33], v[32:33], v[228:229]
	v_pk_add_f32 v[26:27], v[26:27], v[236:237]
	v_pk_add_f32 v[28:29], v[28:29], v[238:239]
	global_store_dwordx4 v156, v[30:33], s[48:49]
	global_store_dwordx4 v156, v[26:29], s[48:49] offset:16
	v_pk_mul_f32 v[226:227], v[54:55], v[30:31]
	v_pk_mul_f32 v[228:229], v[56:57], v[32:33]
	v_pk_mul_f32 v[236:237], v[50:51], v[26:27]
	v_pk_mul_f32 v[238:239], v[52:53], v[28:29]
	v_cvt_pk_bf16_f32 v188, v226, v227
	v_cvt_pk_bf16_f32 v189, v228, v229
	v_cvt_pk_bf16_f32 v190, v236, v237
	v_cvt_pk_bf16_f32 v191, v238, v239
	v_lshrrev_b32_e32 v202, 1, v156
	global_store_dwordx4 v202, v[188:191], s[46:47]
	v_mul_f32_e32 v196, v30, v30
	v_fmac_f32_e32 v196, v31, v31
	v_fmac_f32_e32 v196, v32, v32
	v_fmac_f32_e32 v196, v33, v33
	v_fmac_f32_e32 v196, v26, v26
	v_fmac_f32_e32 v196, v27, v27
	v_fmac_f32_e32 v196, v28, v28
	v_fmac_f32_e32 v196, v29, v29
	s_waitcnt vmcnt(18)
	v_pk_add_f32 v[22:23], v[22:23], v[240:241]
	v_pk_add_f32 v[24:25], v[24:25], v[242:243]
	v_pk_add_f32 v[18:19], v[18:19], v[244:245]
	v_pk_add_f32 v[20:21], v[20:21], v[246:247]
	global_store_dwordx4 v156, v[22:25], s[48:49] offset:512
	global_store_dwordx4 v156, v[18:21], s[48:49] offset:528
	v_pk_mul_f32 v[240:241], v[46:47], v[22:23]
	v_pk_mul_f32 v[242:243], v[48:49], v[24:25]
	v_pk_mul_f32 v[244:245], v[42:43], v[18:19]
	v_pk_mul_f32 v[246:247], v[44:45], v[20:21]
	v_cvt_pk_bf16_f32 v192, v240, v241
	v_cvt_pk_bf16_f32 v193, v242, v243
	v_cvt_pk_bf16_f32 v194, v244, v245
	v_cvt_pk_bf16_f32 v195, v246, v247
	global_store_dwordx4 v202, v[192:195], s[46:47] offset:256
	v_fmac_f32_e32 v196, v22, v22
	v_fmac_f32_e32 v196, v23, v23
	v_fmac_f32_e32 v196, v24, v24
	v_fmac_f32_e32 v196, v25, v25
	v_fmac_f32_e32 v196, v18, v18
	v_fmac_f32_e32 v196, v19, v19
	v_fmac_f32_e32 v196, v20, v20
	v_fmac_f32_e32 v196, v21, v21
	v_mov_b32_e32 v198, v196
	s_nop 1
	v_permlane16_swap_b32_e32 v196, v198
	v_add_f32_e32 v196, v196, v198
	v_mov_b32_e32 v198, v196
	s_nop 1
	v_permlane32_swap_b32_e32 v196, v198
	v_add_f32_e32 v196, v196, v198
	v_add_u32_e32 v200, 0x5000, v201
	s_mov_b64 exec, s[38:39]
	global_store_dword v200, v196, s[22:23]
	s_mov_b64 exec, -1
	s_waitcnt vmcnt(16)
	v_pk_add_f32 v[14:15], v[14:15], v[180:181]
	v_pk_add_f32 v[16:17], v[16:17], v[182:183]
	v_pk_add_f32 v[10:11], v[10:11], v[184:185]
	v_pk_add_f32 v[12:13], v[12:13], v[186:187]
	global_store_dwordx4 v157, v[14:17], s[48:49]
	global_store_dwordx4 v157, v[10:13], s[48:49] offset:16
	v_pk_mul_f32 v[180:181], v[54:55], v[14:15]
	v_pk_mul_f32 v[182:183], v[56:57], v[16:17]
	v_pk_mul_f32 v[184:185], v[50:51], v[10:11]
	v_pk_mul_f32 v[186:187], v[52:53], v[12:13]
	v_cvt_pk_bf16_f32 v188, v180, v181
	v_cvt_pk_bf16_f32 v189, v182, v183
	v_cvt_pk_bf16_f32 v190, v184, v185
	v_cvt_pk_bf16_f32 v191, v186, v187
	v_lshrrev_b32_e32 v203, 1, v157
	global_store_dwordx4 v203, v[188:191], s[46:47]
	v_mul_f32_e32 v197, v14, v14
	v_fmac_f32_e32 v197, v15, v15
	v_fmac_f32_e32 v197, v16, v16
	v_fmac_f32_e32 v197, v17, v17
	v_fmac_f32_e32 v197, v10, v10
	v_fmac_f32_e32 v197, v11, v11
	v_fmac_f32_e32 v197, v12, v12
	v_fmac_f32_e32 v197, v13, v13
	s_waitcnt vmcnt(14)
	v_pk_add_f32 v[6:7], v[6:7], v[210:211]
	v_pk_add_f32 v[8:9], v[8:9], v[212:213]
	v_pk_add_f32 v[2:3], v[2:3], v[214:215]
	v_pk_add_f32 v[4:5], v[4:5], v[216:217]
	global_store_dwordx4 v157, v[6:9], s[48:49] offset:512
	global_store_dwordx4 v157, v[2:5], s[48:49] offset:528
	v_pk_mul_f32 v[210:211], v[46:47], v[6:7]
	v_pk_mul_f32 v[212:213], v[48:49], v[8:9]
	v_pk_mul_f32 v[214:215], v[42:43], v[2:3]
	v_pk_mul_f32 v[216:217], v[44:45], v[4:5]
	v_cvt_pk_bf16_f32 v192, v210, v211
	v_cvt_pk_bf16_f32 v193, v212, v213
	v_cvt_pk_bf16_f32 v194, v214, v215
	v_cvt_pk_bf16_f32 v195, v216, v217
	global_store_dwordx4 v203, v[192:195], s[46:47] offset:256
	v_fmac_f32_e32 v197, v6, v6
	v_fmac_f32_e32 v197, v7, v7
	v_fmac_f32_e32 v197, v8, v8
	v_fmac_f32_e32 v197, v9, v9
	v_fmac_f32_e32 v197, v2, v2
	v_fmac_f32_e32 v197, v3, v3
	v_fmac_f32_e32 v197, v4, v4
	v_fmac_f32_e32 v197, v5, v5
	v_mov_b32_e32 v198, v197
	s_nop 1
	v_permlane16_swap_b32_e32 v197, v198
	v_add_f32_e32 v197, v197, v198
	v_mov_b32_e32 v198, v197
	s_nop 1
	v_permlane32_swap_b32_e32 v197, v198
	v_add_f32_e32 v197, v197, v198
	v_add_u32_e32 v200, 0x5800, v201
	s_mov_b64 exec, s[38:39]
	global_store_dword v200, v197, s[22:23]
	s_mov_b64 exec, -1
	s_branch .Lres_h_tail
.Lres_h_nocopy:
	v_mov_b32_e32 v154, v199
	global_load_dwordx4 v[210:213], v154, s[48:49]
	global_load_dwordx4 v[214:217], v154, s[48:49] offset:16
	global_load_dwordx4 v[218:221], v154, s[48:49] offset:512
	global_load_dwordx4 v[222:225], v154, s[48:49] offset:528
	v_add_u32_e32 v155, 0x20000, v199
	global_load_dwordx4 v[226:229], v155, s[48:49]
	global_load_dwordx4 v[236:239], v155, s[48:49] offset:16
	global_load_dwordx4 v[240:243], v155, s[48:49] offset:512
	global_load_dwordx4 v[244:247], v155, s[48:49] offset:528
	v_add_u32_e32 v156, 0x40000, v199
	global_load_dwordx4 v[180:183], v156, s[48:49]
	global_load_dwordx4 v[184:187], v156, s[48:49] offset:16
	s_waitcnt vmcnt(8)
	v_pk_add_f32 v[142:143], v[142:143], v[210:211]
	v_pk_add_f32 v[144:145], v[144:145], v[212:213]
	v_pk_add_f32 v[138:139], v[138:139], v[214:215]
	v_pk_add_f32 v[140:141], v[140:141], v[216:217]
	global_store_dwordx4 v154, v[142:145], s[48:49]
	global_store_dwordx4 v154, v[138:141], s[48:49] offset:16
	global_load_dwordx4 v[210:213], v156, s[48:49] offset:512
	global_load_dwordx4 v[214:217], v156, s[48:49] offset:528
	s_waitcnt vmcnt(10)
	v_pk_add_f32 v[134:135], v[134:135], v[218:219]
	v_pk_add_f32 v[136:137], v[136:137], v[220:221]
	v_pk_add_f32 v[130:131], v[130:131], v[222:223]
	v_pk_add_f32 v[132:133], v[132:133], v[224:225]
	global_store_dwordx4 v154, v[134:137], s[48:49] offset:512
	global_store_dwordx4 v154, v[130:133], s[48:49] offset:528
	v_add_u32_e32 v157, 0x60000, v199
	global_load_dwordx4 v[218:221], v157, s[48:49]
	global_load_dwordx4 v[222:225], v157, s[48:49] offset:16
	s_waitcnt vmcnt(12)
	v_pk_add_f32 v[126:127], v[126:127], v[226:227]
	v_pk_add_f32 v[128:129], v[128:129], v[228:229]
	v_pk_add_f32 v[122:123], v[122:123], v[236:237]
	v_pk_add_f32 v[124:125], v[124:125], v[238:239]
	global_store_dwordx4 v155, v[126:129], s[48:49]
	global_store_dwordx4 v155, v[122:125], s[48:49] offset:16
	global_load_dwordx4 v[226:229], v157, s[48:49] offset:512
	global_load_dwordx4 v[236:239], v157, s[48:49] offset:528
	s_waitcnt vmcnt(14)
	v_pk_add_f32 v[118:119], v[118:119], v[240:241]
	v_pk_add_f32 v[120:121], v[120:121], v[242:243]
	v_pk_add_f32 v[114:115], v[114:115], v[244:245]
	v_pk_add_f32 v[116:117], v[116:117], v[246:247]
	global_store_dwordx4 v155, v[118:121], s[48:49] offset:512
	global_store_dwordx4 v155, v[114:117], s[48:49] offset:528
	v_add_u32_e32 v154, 0x100000, v199
	global_load_dwordx4 v[240:243], v154, s[48:49]
	global_load_dwordx4 v[244:247], v154, s[48:49] offset:16
	s_waitcnt vmcnt(16)
	v_pk_add_f32 v[110:111], v[110:111], v[180:181]
	v_pk_add_f32 v[112:113], v[112:113], v[182:183]
	v_pk_add_f32 v[106:107], v[106:107], v[184:185]
	v_pk_add_f32 v[108:109], v[108:109], v[186:187]
	global_store_dwordx4 v156, v[110:113], s[48:49]
	global_store_dwordx4 v156, v[106:109], s[48:49] offset:16
	global_load_dwordx4 v[180:183], v154, s[48:49] offset:512
	global_load_dwordx4 v[184:187], v154, s[48:49] offset:528
	s_waitcnt vmcnt(16)
	v_pk_add_f32 v[102:103], v[102:103], v[210:211]
	v_pk_add_f32 v[104:105], v[104:105], v[212:213]
	v_pk_add_f32 v[98:99], v[98:99], v[214:215]
	v_pk_add_f32 v[100:101], v[100:101], v[216:217]
	global_store_dwordx4 v156, v[102:105], s[48:49] offset:512
	global_store_dwordx4 v156, v[98:101], s[48:49] offset:528
	v_add_u32_e32 v155, 0x120000, v199
	global_load_dwordx4 v[210:213], v155, s[48:49]
	global_load_dwordx4 v[214:217], v155, s[48:49] offset:16
	s_waitcnt vmcnt(16)
	v_pk_add_f32 v[94:95], v[94:95], v[218:219]
	v_pk_add_f32 v[96:97], v[96:97], v[220:221]
	v_pk_add_f32 v[90:91], v[90:91], v[222:223]
	v_pk_add_f32 v[92:93], v[92:93], v[224:225]
	global_store_dwordx4 v157, v[94:97], s[48:49]
	global_store_dwordx4 v157, v[90:93], s[48:49] offset:16
	global_load_dwordx4 v[218:221], v155, s[48:49] offset:512
	global_load_dwordx4 v[222:225], v155, s[48:49] offset:528
	s_waitcnt vmcnt(16)
	v_pk_add_f32 v[86:87], v[86:87], v[226:227]
	v_pk_add_f32 v[88:89], v[88:89], v[228:229]
	v_pk_add_f32 v[82:83], v[82:83], v[236:237]
	v_pk_add_f32 v[84:85], v[84:85], v[238:239]
	global_store_dwordx4 v157, v[86:89], s[48:49] offset:512
	global_store_dwordx4 v157, v[82:85], s[48:49] offset:528
	v_add_u32_e32 v156, 0x140000, v199
	global_load_dwordx4 v[226:229], v156, s[48:49]
	global_load_dwordx4 v[236:239], v156, s[48:49] offset:16
	s_waitcnt vmcnt(16)
	v_pk_add_f32 v[78:79], v[78:79], v[240:241]
	v_pk_add_f32 v[80:81], v[80:81], v[242:243]
	v_pk_add_f32 v[74:75], v[74:75], v[244:245]
	v_pk_add_f32 v[76:77], v[76:77], v[246:247]
	global_store_dwordx4 v154, v[78:81], s[48:49]
	global_store_dwordx4 v154, v[74:77], s[48:49] offset:16
	global_load_dwordx4 v[240:243], v156, s[48:49] offset:512
	global_load_dwordx4 v[244:247], v156, s[48:49] offset:528
	s_waitcnt vmcnt(16)
	v_pk_add_f32 v[70:71], v[70:71], v[180:181]
	v_pk_add_f32 v[72:73], v[72:73], v[182:183]
	v_pk_add_f32 v[66:67], v[66:67], v[184:185]
	v_pk_add_f32 v[68:69], v[68:69], v[186:187]
	global_store_dwordx4 v154, v[70:73], s[48:49] offset:512
	global_store_dwordx4 v154, v[66:69], s[48:49] offset:528
	v_add_u32_e32 v157, 0x160000, v199
	global_load_dwordx4 v[180:183], v157, s[48:49]
	global_load_dwordx4 v[184:187], v157, s[48:49] offset:16
	s_waitcnt vmcnt(16)
	v_pk_add_f32 v[62:63], v[62:63], v[210:211]
	v_pk_add_f32 v[64:65], v[64:65], v[212:213]
	v_pk_add_f32 v[58:59], v[58:59], v[214:215]
	v_pk_add_f32 v[60:61], v[60:61], v[216:217]
	global_store_dwordx4 v155, v[62:65], s[48:49]
	global_store_dwordx4 v155, v[58:61], s[48:49] offset:16
	global_load_dwordx4 v[210:213], v157, s[48:49] offset:512
	global_load_dwordx4 v[214:217], v157, s[48:49] offset:528
	s_waitcnt vmcnt(16)
	v_pk_add_f32 v[38:39], v[38:39], v[218:219]
	v_pk_add_f32 v[40:41], v[40:41], v[220:221]
	v_pk_add_f32 v[34:35], v[34:35], v[222:223]
	v_pk_add_f32 v[36:37], v[36:37], v[224:225]
	global_store_dwordx4 v155, v[38:41], s[48:49] offset:512
	global_store_dwordx4 v155, v[34:37], s[48:49] offset:528
	s_waitcnt vmcnt(14)
	v_pk_add_f32 v[30:31], v[30:31], v[226:227]
	v_pk_add_f32 v[32:33], v[32:33], v[228:229]
	v_pk_add_f32 v[26:27], v[26:27], v[236:237]
	v_pk_add_f32 v[28:29], v[28:29], v[238:239]
	global_store_dwordx4 v156, v[30:33], s[48:49]
	global_store_dwordx4 v156, v[26:29], s[48:49] offset:16
	s_waitcnt vmcnt(12)
	v_pk_add_f32 v[22:23], v[22:23], v[240:241]
	v_pk_add_f32 v[24:25], v[24:25], v[242:243]
	v_pk_add_f32 v[18:19], v[18:19], v[244:245]
	v_pk_add_f32 v[20:21], v[20:21], v[246:247]
	global_store_dwordx4 v156, v[22:25], s[48:49] offset:512
	global_store_dwordx4 v156, v[18:21], s[48:49] offset:528
	s_waitcnt vmcnt(10)
	v_pk_add_f32 v[14:15], v[14:15], v[180:181]
	v_pk_add_f32 v[16:17], v[16:17], v[182:183]
	v_pk_add_f32 v[10:11], v[10:11], v[184:185]
	v_pk_add_f32 v[12:13], v[12:13], v[186:187]
	global_store_dwordx4 v157, v[14:17], s[48:49]
	global_store_dwordx4 v157, v[10:13], s[48:49] offset:16
	s_waitcnt vmcnt(8)
	v_pk_add_f32 v[6:7], v[6:7], v[210:211]
	v_pk_add_f32 v[8:9], v[8:9], v[212:213]
	v_pk_add_f32 v[2:3], v[2:3], v[214:215]
	v_pk_add_f32 v[4:5], v[4:5], v[216:217]
	global_store_dwordx4 v157, v[6:9], s[48:49] offset:512
	global_store_dwordx4 v157, v[2:5], s[48:49] offset:528
.Lres_h_tail:
	s_and_b64 vcc, exec, s[40:41]
	s_mov_b64 s[22:23], -1
	s_cbranch_vccnz .LBB0_716
.LBB0_780:
	s_andn2_b64 vcc, exec, s[10:11]
	s_cbranch_vccnz .LBB0_715
	s_barrier
	s_branch .LBB0_715
